# phase 0 item assignment rebalanced at the loop edge: blocks owning an ada matvec item take 4 weight-conversion tiles instead of 12, the others ~17
# speedup vs baseline: 1.0031x; 1.0007x over previous
.LBB0_7:
	v_readlane_b32 s16, v253, 0
	s_cmpk_lt_u32 s16, 0xc0
	s_cbranch_scc1 .Lp0_ada
	s_addk_i32 s40, 0x140
	s_cmpk_lt_i32 s40, 0x1641
	s_cbranch_scc1 .LBB0_8
	s_branch .LBB0_92
.Lp0_ada:
	s_cmpk_lt_i32 s40, 0xc0
	s_cbranch_scc0 .Lp0_ada2
	s_addk_i32 s40, 0x1641
	s_branch .Lp0_chk
.Lp0_ada2:
	s_addk_i32 s40, 0xc0
.Lp0_chk:
	s_cmpk_lt_i32 s40, 0x1941
	s_cbranch_scc1 .LBB0_8
	s_branch .LBB0_92
